# phase 3: 64-step chain chunk loop MFMA stages re-written with LDS operand reads issued a tile group ahead (was ds_read/wait/mfma chains), UT loads hoisted to the chunk staging loads; 16-step chain sta
# speedup vs baseline: 1.0133x; 1.0034x over previous
.LBB0_1066:
	s_or_b64 exec, exec, s[0:1]
	s_add_i32 s36, s28, 0xfffffbc0
	s_ashr_i32 s0, s26, 2
	s_and_b32 s29, s28, 15
	v_bfi_b32 v64, -16, s0, v45
	s_and_b32 s0, s36, 0x1fff0
	s_or_b32 s0, s0, s29
	s_lshl_b32 s26, s0, 14
	v_readlane_b32 s64, v253, 21
	v_bfe_u32 v22, v45, 4, 2
	s_lshl_b64 s[0:1], s[26:27], 2
	v_readlane_b32 s74, v253, 31
	v_readlane_b32 s75, v253, 32
	s_add_u32 s10, s74, s0
	v_lshlrev_b32_e32 v6, 2, v22
	v_lshlrev_b32_e32 v127, 9, v22
	s_addc_u32 s11, s75, s1
	v_ashrrev_i32_e32 v65, 31, v64
	v_or_b32_e32 v23, 1, v6
	v_or_b32_e32 v21, 2, v6
	v_or_b32_e32 v24, 3, v6
	v_or_b32_e32 v6, 0x800, v127
	v_lshl_add_u64 v[26:27], v[64:65], 2, s[10:11]
	v_lshlrev_b32_e32 v124, 11, v22
	v_lshlrev_b32_e32 v66, 2, v6
	v_or_b32_e32 v6, 0x880, v127
	v_or_b32_e32 v20, 0x2100, v127
	v_lshl_add_u64 v[0:1], v[26:27], 0, v[124:125]
	v_lshlrev_b32_e32 v124, 9, v23
	v_lshlrev_b32_e32 v68, 2, v6
	v_or_b32_e32 v6, 0x900, v127
	v_lshlrev_b32_e32 v94, 2, v20
	v_or_b32_e32 v20, 0x2180, v127
	v_lshl_add_u64 v[2:3], v[26:27], 0, v[124:125]
	v_lshlrev_b32_e32 v124, 9, v21
	v_mov_b32_e32 v69, v125
	v_lshlrev_b32_e32 v70, 2, v6
	v_or_b32_e32 v6, 0x980, v127
	v_lshlrev_b32_e32 v96, 2, v20
	v_or_b32_e32 v20, 0x2800, v127
	v_lshl_add_u64 v[4:5], v[26:27], 0, v[124:125]
	v_lshlrev_b32_e32 v124, 9, v24
	v_mov_b32_e32 v67, v125
	v_lshl_add_u64 v[12:13], v[26:27], 0, v[68:69]
	v_mov_b32_e32 v71, v125
	v_lshlrev_b32_e32 v72, 2, v6
	v_mov_b32_e32 v73, v125
	v_lshlrev_b32_e32 v98, 2, v20
	v_or_b32_e32 v20, 0x2880, v127
	v_lshl_add_u64 v[8:9], v[26:27], 0, v[124:125]
	v_lshl_add_u64 v[10:11], v[26:27], 0, v[66:67]
	v_lshl_add_u64 v[14:15], v[26:27], 0, v[70:71]
	v_lshl_add_u64 v[16:17], v[26:27], 0, v[72:73]
	global_load_dword v0, v[0:1], off
	s_nop 0
	global_load_dword v1, v[2:3], off
	global_load_dword v6, v[4:5], off
	global_load_dword v7, v[8:9], off
	s_nop 0
	global_load_dword v2, v[10:11], off
	global_load_dword v3, v[12:13], off
	global_load_dword v4, v[14:15], off
	global_load_dword v5, v[16:17], off
	v_or_b32_e32 v12, 0x1100, v127
	v_lshlrev_b32_e32 v100, 2, v20
	v_or_b32_e32 v20, 0x2900, v127
	v_lshlrev_b32_e32 v78, 2, v12
	v_or_b32_e32 v12, 0x1180, v127
	v_lshlrev_b32_e32 v102, 2, v20
	v_or_b32_e32 v20, 0x2980, v127
	v_lshlrev_b32_e32 v80, 2, v12
	v_or_b32_e32 v12, 0x1800, v127
	v_lshlrev_b32_e32 v104, 2, v20
	v_or_b32_e32 v20, 0x3000, v127
	v_lshlrev_b32_e32 v82, 2, v12
	v_or_b32_e32 v12, 0x1880, v127
	v_lshlrev_b32_e32 v106, 2, v20
	v_or_b32_e32 v20, 0x3080, v127
	v_or_b32_e32 v8, 0x1000, v127
	v_or_b32_e32 v10, 0x1080, v127
	v_lshlrev_b32_e32 v84, 2, v12
	v_or_b32_e32 v12, 0x1900, v127
	v_lshlrev_b32_e32 v108, 2, v20
	v_or_b32_e32 v20, 0x3100, v127
	v_lshlrev_b32_e32 v74, 2, v8
	v_mov_b32_e32 v75, v125
	v_lshlrev_b32_e32 v76, 2, v10
	v_mov_b32_e32 v77, v125
	v_mov_b32_e32 v79, v125
	v_mov_b32_e32 v81, v125
	v_mov_b32_e32 v83, v125
	v_lshlrev_b32_e32 v86, 2, v12
	v_or_b32_e32 v12, 0x1980, v127
	v_lshlrev_b32_e32 v110, 2, v20
	v_or_b32_e32 v20, 0x3180, v127
	v_lshl_add_u64 v[8:9], v[26:27], 0, v[74:75]
	v_lshl_add_u64 v[10:11], v[26:27], 0, v[76:77]
	v_lshl_add_u64 v[14:15], v[26:27], 0, v[78:79]
	v_lshl_add_u64 v[16:17], v[26:27], 0, v[80:81]
	v_lshl_add_u64 v[18:19], v[26:27], 0, v[82:83]
	v_mov_b32_e32 v85, v125
	v_mov_b32_e32 v87, v125
	v_lshlrev_b32_e32 v88, 2, v12
	v_mov_b32_e32 v89, v125
	v_lshlrev_b32_e32 v112, 2, v20
	v_or_b32_e32 v20, 0x3800, v127
	v_lshl_add_u64 v[28:29], v[26:27], 0, v[84:85]
	v_lshl_add_u64 v[30:31], v[26:27], 0, v[86:87]
	v_lshl_add_u64 v[32:33], v[26:27], 0, v[88:89]
	global_load_dword v12, v[8:9], off
	global_load_dword v13, v[10:11], off
	s_nop 0
	global_load_dword v14, v[14:15], off
	s_nop 0
	global_load_dword v15, v[16:17], off
	global_load_dword v8, v[18:19], off
	global_load_dword v9, v[28:29], off
	global_load_dword v10, v[30:31], off
	global_load_dword v11, v[32:33], off
	v_or_b32_e32 v16, 0x2000, v127
	v_or_b32_e32 v18, 0x2080, v127
	v_lshlrev_b32_e32 v114, 2, v20
	v_or_b32_e32 v20, 0x3880, v127
	v_lshlrev_b32_e32 v90, 2, v16
	v_mov_b32_e32 v91, v125
	v_lshlrev_b32_e32 v92, 2, v18
	v_mov_b32_e32 v93, v125
	v_mov_b32_e32 v95, v125
	v_mov_b32_e32 v99, v125
	v_mov_b32_e32 v101, v125
	v_mov_b32_e32 v103, v125
	v_mov_b32_e32 v105, v125
	v_lshlrev_b32_e32 v116, 2, v20
	v_or_b32_e32 v20, 0x3900, v127
	v_lshl_add_u64 v[16:17], v[26:27], 0, v[90:91]
	v_lshl_add_u64 v[18:19], v[26:27], 0, v[92:93]
	v_lshl_add_u64 v[28:29], v[26:27], 0, v[94:95]
	v_mov_b32_e32 v97, v125
	v_lshl_add_u64 v[32:33], v[26:27], 0, v[98:99]
	v_lshl_add_u64 v[34:35], v[26:27], 0, v[100:101]
	v_lshl_add_u64 v[36:37], v[26:27], 0, v[102:103]
	v_lshl_add_u64 v[38:39], v[26:27], 0, v[104:105]
	v_mov_b32_e32 v107, v125
	v_mov_b32_e32 v111, v125
	v_mov_b32_e32 v113, v125
	v_lshlrev_b32_e32 v118, 2, v20
	v_or_b32_e32 v20, 0x3980, v127
	v_lshl_add_u64 v[30:31], v[26:27], 0, v[96:97]
	global_load_dword v16, v[16:17], off
	s_nop 0
	global_load_dword v17, v[18:19], off
	s_nop 0
	global_load_dword v18, v[28:29], off
	global_load_dword v19, v[30:31], off
	s_nop 0
	global_load_dword v32, v[32:33], off
	s_nop 0
	global_load_dword v33, v[34:35], off
	s_nop 0
	global_load_dword v34, v[36:37], off
	global_load_dword v35, v[38:39], off
	v_lshl_add_u64 v[28:29], v[26:27], 0, v[106:107]
	v_mov_b32_e32 v109, v125
	v_lshl_add_u64 v[36:37], v[26:27], 0, v[110:111]
	v_lshl_add_u64 v[38:39], v[26:27], 0, v[112:113]
	v_mov_b32_e32 v115, v125
	v_mov_b32_e32 v117, v125
	v_mov_b32_e32 v119, v125
	v_lshlrev_b32_e32 v120, 2, v20
	v_mov_b32_e32 v121, v125
	v_lshl_add_u64 v[30:31], v[26:27], 0, v[108:109]
	v_lshl_add_u64 v[46:47], v[26:27], 0, v[114:115]
	v_lshl_add_u64 v[48:49], v[26:27], 0, v[116:117]
	v_lshl_add_u64 v[50:51], v[26:27], 0, v[118:119]
	v_lshl_add_u64 v[26:27], v[26:27], 0, v[120:121]
	global_load_dword v40, v[28:29], off
	global_load_dword v41, v[30:31], off
	global_load_dword v42, v[36:37], off
	global_load_dword v43, v[38:39], off
	s_nop 0
	global_load_dword v36, v[46:47], off
	global_load_dword v37, v[48:49], off
	global_load_dword v38, v[50:51], off
	global_load_dword v39, v[26:27], off
	v_mul_lo_u32 v20, v64, s15
	v_add_u32_e32 v25, 0, v20
	v_lshlrev_b32_e32 v20, 3, v22
	v_add_u32_e32 v30, v25, v20
	s_waitcnt vmcnt(30)
	v_cvt_pk_bf16_f32 v26, v0, v1
	s_waitcnt vmcnt(28)
	v_cvt_pk_bf16_f32 v27, v6, v7
	s_waitcnt vmcnt(26)
	v_cvt_pk_bf16_f32 v28, v2, v3
	s_waitcnt vmcnt(24)
	v_cvt_pk_bf16_f32 v29, v4, v5
	v_add_u32_e32 v46, 0xf000, v30
	s_mul_i32 s10, s36, 0x5400
	ds_write2_b64 v46, v[26:27], v[28:29] offset0:128 offset1:132
	s_add_u32 s30, s9, s10
	s_mov_b32 s37, s27
	s_addc_u32 s31, s16, 0
	s_lshl_b64 s[10:11], s[36:37], 2
	s_add_u32 s10, s96, s10
	s_addc_u32 s11, s97, s11
	v_readlane_b32 s65, v253, 22
	v_readlane_b32 s66, v253, 23
	v_readlane_b32 s67, v253, 24
	v_readlane_b32 s68, v253, 25
	v_readlane_b32 s69, v253, 26
	v_readlane_b32 s70, v253, 27
	v_readlane_b32 s71, v253, 28
	v_readlane_b32 s72, v253, 29
	v_readlane_b32 s73, v253, 30
	v_readlane_b32 s76, v253, 33
	v_readlane_b32 s77, v253, 34
	s_waitcnt vmcnt(22)
	v_cvt_pk_bf16_f32 v26, v12, v13
	v_readlane_b32 s78, v253, 35
	s_waitcnt vmcnt(20)
	v_cvt_pk_bf16_f32 v27, v14, v15
	v_readlane_b32 s79, v253, 36
	s_waitcnt vmcnt(18)
	v_cvt_pk_bf16_f32 v28, v8, v9
	s_waitcnt vmcnt(16)
	v_cvt_pk_bf16_f32 v29, v10, v11
	ds_write2_b64 v46, v[26:27], v[28:29] offset0:136 offset1:140
	s_waitcnt vmcnt(14)
	v_cvt_pk_bf16_f32 v26, v16, v17
	s_waitcnt vmcnt(12)
	v_cvt_pk_bf16_f32 v27, v18, v19
	s_waitcnt vmcnt(10)
	v_cvt_pk_bf16_f32 v28, v32, v33
	s_waitcnt vmcnt(8)
	v_cvt_pk_bf16_f32 v29, v34, v35
	ds_write2_b64 v46, v[26:27], v[28:29] offset0:144 offset1:148
	s_waitcnt vmcnt(6)
	v_cvt_pk_bf16_f32 v26, v40, v41
	s_waitcnt vmcnt(4)
	v_cvt_pk_bf16_f32 v27, v42, v43
	s_waitcnt vmcnt(2)
	v_cvt_pk_bf16_f32 v28, v36, v37
	s_waitcnt vmcnt(0)
	v_cvt_pk_bf16_f32 v29, v38, v39
	ds_write2_b64 v46, v[26:27], v[28:29] offset0:152 offset1:156
	global_load_dword v44, v161, s[10:11] sc1
	s_movk_i32 s10, 0x100
	v_cmp_gt_i32_e32 vcc, s10, v45
	v_lshlrev_b32_e32 v26, 4, v45
	s_waitcnt lgkmcnt(0)
	s_barrier
	s_mov_b64 s[38:39], exec
	v_lshlrev_b32_e32 v30, 4, v45
	v_mov_b32_e32 v31, 0
	v_ashrrev_i32_e32 v29, 4, v45
	v_and_b32_e32 v47, 0xf0, v30
	v_mad_u32_u24 v29, v29, s15, v47
	v_lshrrev_b32_e32 v47, 2, v45
	v_lshl_add_u32 v47, v47, 4, v30
	s_add_u32 s34, s30, 0x2000
	s_addc_u32 s35, s31, 0
	s_and_b64 exec, s[38:39], vcc
	v_lshl_add_u64 v[52:53], s[30:31], 0, v[30:31]
	global_load_dwordx4 v[48:51], v[52:53], off
	v_lshl_add_u64 v[52:53], s[34:35], 0, v[30:31]
	global_load_dwordx4 v[232:235], v[52:53], off
	s_add_u32 s34, s30, 0x3000
	s_addc_u32 s35, s31, 0
	v_cmp_gt_i32_e32 vcc, 64, v45
	s_nop 1
	s_and_b64 exec, s[38:39], vcc
	v_lshl_add_u64 v[52:53], s[34:35], 0, v[30:31]
	global_load_dwordx4 v[236:239], v[52:53], off
	s_mov_b64 exec, s[38:39]
	s_add_u32 s34, s30, 0x3400
	s_addc_u32 s35, s31, 0
	v_lshl_add_u64 v[52:53], s[34:35], 0, v[30:31]
	global_load_dwordx4 v[240:243], v[52:53], off
	v_and_b32_e32 v27, 15, v45
	v_lshlrev_b32_e32 v71, 7, v23
	v_lshlrev_b32_e32 v69, 7, v21
	v_lshlrev_b32_e32 v67, 7, v24
	v_mul_u32_u24_e32 v28, 0x110, v27
	v_mul_u32_u24_e32 v24, 0x50, v27
	v_mul_i32_i24_e32 v27, 0xffffff40, v27
	s_movk_i32 s10, 0x100
	v_cmp_gt_i32_e32 vcc, s10, v45
	s_nop 1
	s_and_b64 exec, s[38:39], vcc
	s_waitcnt vmcnt(3)
	ds_write_b128 v29, v[48:51]
	s_waitcnt vmcnt(2)
	ds_write_b128 v29, v[232:235] offset:17408
	v_cmp_gt_i32_e32 vcc, 64, v45
	s_nop 1
	s_and_b64 exec, s[38:39], vcc
	s_waitcnt vmcnt(1)
	ds_write_b128 v47, v[236:239] offset:34816
	s_mov_b64 exec, s[38:39]
	s_waitcnt vmcnt(0)
	ds_write_b128 v47, v[240:243] offset:44032
	s_movk_i32 s26, 0xfe3f
	s_mov_b64 s[10:11], exec
	v_lshlrev_b64 v[30:31], 5, v[64:65]
	v_mov_b32_e32 v21, v125
	v_lshl_add_u64 v[30:31], s[30:31], 0, v[30:31]
	v_lshl_add_u64 v[30:31], v[30:31], 0, v[20:21]
	v_add_co_u32_e32 v30, vcc, 0x1000, v30
	v_lshlrev_b32_e32 v47, 4, v22
	s_nop 0
	v_addc_co_u32_e32 v31, vcc, 0, v31, vcc
	global_load_dwordx2 v[122:123], v[30:31], off
	v_add_u32_e32 v73, 0, v47
	v_add_u32_e32 v26, v73, v28
	s_waitcnt lgkmcnt(0)
	s_barrier
	ds_read_b128 v[28:31], v26
	v_add_u32_e32 v21, v25, v47
	ds_read_b128 v[48:51], v26 offset:64
	ds_read_b128 v[52:55], v21 offset:62464
	ds_read_b128 v[56:59], v21 offset:62528
	s_waitcnt lgkmcnt(1)
	v_mfma_f32_16x16x32_bf16 v[28:31], v[28:31], v[52:55], 0
	ds_read_b128 v[60:63], v26 offset:128
	ds_read_b128 v[130:133], v26 offset:192
	s_movk_i32 s10, 0x50
	v_add_u32_e32 v73, v73, v24
	s_waitcnt lgkmcnt(2)
	v_mfma_f32_16x16x32_bf16 v[28:31], v[48:51], v[56:59], v[28:31]
	ds_read_b128 v[48:51], v21 offset:62592
	ds_read_b128 v[134:137], v21 offset:62656
	v_mul_lo_u32 v21, v64, s10
	v_add_u32_e32 v25, s8, v21
	s_waitcnt lgkmcnt(1)
	v_mfma_f32_16x16x32_bf16 v[28:31], v[60:63], v[48:51], v[28:31]
	v_add_u32_e32 v62, v25, v20
	s_movk_i32 s10, 0x440
	s_waitcnt vmcnt(1)
	v_pk_mul_f32 v[4:5], v[4:5], v[44:45] op_sel_hi:[1,0]
	s_waitcnt lgkmcnt(0)
	v_mfma_f32_16x16x32_bf16 v[28:31], v[130:133], v[134:137], v[28:31]
	v_mul_f32_e64 v2, v2, v44
	v_mul_f32_e64 v3, v3, v44
	v_pk_mul_f32 v[14:15], v[14:15], v[44:45] op_sel_hi:[1,0]
	v_pk_mul_f32 v[12:13], v[12:13], v[44:45] op_sel_hi:[1,0]
	s_waitcnt vmcnt(0)
	v_lshlrev_b32_e32 v20, 16, v122
	v_and_b32_e32 v21, 0xffff0000, v122
	v_lshlrev_b32_e32 v60, 16, v123
	v_and_b32_e32 v61, 0xffff0000, v123
	v_pk_add_f32 v[20:21], v[20:21], v[28:29] neg_lo:[0,1] neg_hi:[0,1]
	v_pk_add_f32 v[28:29], v[60:61], v[30:31] neg_lo:[0,1] neg_hi:[0,1]
	v_cvt_pk_bf16_f32 v20, v20, v21
	v_cvt_pk_bf16_f32 v21, v28, v29
	ds_write_b64 v62, v[20:21]
	s_waitcnt lgkmcnt(0)
	s_barrier
	ds_read_b128 v[28:31], v26 offset:17408
	ds_read_b128 v[60:63], v26 offset:17472
	s_waitcnt lgkmcnt(1)
	v_mfma_f32_16x16x32_bf16 v[28:31], v[28:31], v[52:55], 0
	ds_read_b128 v[52:55], v26 offset:17536
	v_add_u32_e32 v20, v26, v27
	v_add_u32_e32 v21, v25, v47
	s_waitcnt lgkmcnt(1)
	v_mfma_f32_16x16x32_bf16 v[28:31], v[60:63], v[56:59], v[28:31]
	ds_read_b128 v[56:59], v26 offset:17600
	ds_read_b128 v[60:63], v20 offset:34816
	v_ashrrev_i32_e32 v47, 3, v45
	s_waitcnt lgkmcnt(2)
	v_mfma_f32_16x16x32_bf16 v[26:29], v[52:55], v[48:51], v[28:31]
	ds_read_b128 v[48:51], v21
	v_lshl_add_u32 v20, v64, 1, 0
	v_mad_u32_u24 v25, v22, s10, v20
	s_waitcnt lgkmcnt(2)
	v_mfma_f32_16x16x32_bf16 v[26:29], v[56:59], v[134:137], v[26:29]
	v_mad_u32_u24 v30, v23, s15, v20
	v_cmp_gt_i32_e32 vcc, 16, v47
	s_waitcnt lgkmcnt(0)
	v_mfma_f32_16x16x32_bf16 v[20:23], v[60:63], v[48:51], v[26:29]
	s_nop 3
	v_mul_f32_e64 v26, v6, v44
	v_mul_f32_e64 v27, v7, v44
	s_nop 1
	v_cvt_pk_bf16_f32 v20, v20, s0
	v_cvt_pk_bf16_f32 v21, v21, s0
	v_cvt_pk_bf16_f32 v22, v22, s0
	v_cvt_pk_bf16_f32 v23, v23, s0
	ds_write_b16 v25, v20
	ds_write_b16 v30, v21
	ds_write_b16 v30, v22 offset:272
	ds_write_b16 v30, v23 offset:544
	ds_read_b128 v[20:23], v73 offset:44032
	ds_read_b128 v[52:55], v73 offset:45312
	v_pk_mul_f32 v[24:25], v[0:1], v[44:45] op_sel_hi:[1,0]
	ds_read_b128 v[56:59], v73 offset:46592
	ds_read_b128 v[60:63], v73 offset:47872
	s_waitcnt lgkmcnt(3)
	v_mfma_f32_16x16x32_bf16 v[28:31], v[20:23], v[48:51], v[24:27]
	v_mul_f32_e64 v0, v8, v44
	v_mul_f32_e64 v1, v9, v44
	v_pk_mul_f32 v[8:9], v[16:17], v[44:45] op_sel_hi:[1,0]
	s_waitcnt lgkmcnt(2)
	v_mfma_f32_16x16x32_bf16 v[24:27], v[52:55], v[48:51], v[2:5]
	ds_read_b128 v[52:55], v73 offset:50432
	s_nop 1
	ds_read_b128 v[4:7], v73 offset:49152
	v_pk_mul_f32 v[2:3], v[10:11], v[44:45] op_sel_hi:[1,0]
	v_pk_mul_f32 v[10:11], v[18:19], v[44:45] op_sel_hi:[1,0]
	s_waitcnt lgkmcnt(3)
	v_mfma_f32_16x16x32_bf16 v[20:23], v[56:59], v[48:51], v[12:15]
	s_waitcnt lgkmcnt(2)
	v_mfma_f32_16x16x32_bf16 v[16:19], v[60:63], v[48:51], v[0:3]
	s_nop 2
	v_mul_f32_e64 v2, v34, v44
	v_mul_f32_e64 v3, v35, v44
	v_pk_mul_f32 v[0:1], v[32:33], v[44:45] op_sel_hi:[1,0]
	ds_read_b128 v[32:35], v73 offset:51712
	s_waitcnt lgkmcnt(1)
	v_mfma_f32_16x16x32_bf16 v[12:15], v[4:7], v[48:51], v[8:11]
	v_mul_f32_e64 v6, v42, v44
	v_mul_f32_e64 v7, v43, v44
	v_pk_mul_f32 v[4:5], v[40:41], v[44:45] op_sel_hi:[1,0]
	ds_read_b128 v[40:43], v73 offset:52992
	v_mfma_f32_16x16x32_bf16 v[8:11], v[52:55], v[48:51], v[0:3]
	s_waitcnt lgkmcnt(0)
	s_barrier
	s_nop 0
	v_pk_mul_f32 v[2:3], v[38:39], v[44:45] op_sel_hi:[1,0]
	v_pk_mul_f32 v[0:1], v[36:37], v[44:45] op_sel_hi:[1,0]
	v_mfma_f32_16x16x32_bf16 v[4:7], v[32:35], v[48:51], v[4:7]
	v_cvt_pk_bf16_f32 v32, v28, v29
	v_cvt_pk_bf16_f32 v33, v30, v31
	v_cvt_pk_bf16_f32 v34, v24, v25
	v_mfma_f32_16x16x32_bf16 v[0:3], v[40:43], v[48:51], v[0:3]
	v_cvt_pk_bf16_f32 v35, v26, v27
	v_cvt_pk_bf16_f32 v36, v20, v21
	v_cvt_pk_bf16_f32 v37, v22, v23
	v_cvt_pk_bf16_f32 v38, v16, v17
	v_cvt_pk_bf16_f32 v39, v18, v19
	v_cvt_pk_bf16_f32 v40, v12, v13
	v_cvt_pk_bf16_f32 v41, v14, v15
	v_cvt_pk_bf16_f32 v42, v8, v9
	v_cvt_pk_bf16_f32 v43, v10, v11
	v_cvt_pk_bf16_f32 v48, v4, v5
	v_cvt_pk_bf16_f32 v49, v6, v7
	v_cvt_pk_bf16_f32 v50, v0, v1
	v_cvt_pk_bf16_f32 v51, v2, v3
	ds_write2_b64 v46, v[32:33], v[34:35] offset0:128 offset1:132
	ds_write2_b64 v46, v[36:37], v[38:39] offset0:136 offset1:140
	ds_write2_b64 v46, v[40:41], v[42:43] offset0:144 offset1:148
	ds_write2_b64 v46, v[48:49], v[50:51] offset0:152 offset1:156
	s_and_saveexec_b64 s[30:31], vcc
	s_cbranch_execz .LBB0_1077
	s_and_b32 s10, s36, 0xffffdff0
	v_add_u32_e32 v32, s10, v47
	v_add_u32_e32 v32, 0x2000, v32
	v_and_b32_e32 v36, 7, v45
	v_ashrrev_i32_e32 v33, 31, v32
	v_lshlrev_b64 v[32:33], 11, v[32:33]
	s_lshl_b32 s10, s29, 7
	v_lshlrev_b32_e32 v34, 4, v36
	v_or3_b32 v32, v32, s10, v34
	v_mul_lo_u32 v37, v47, s15
	v_lshlrev_b32_e32 v38, 5, v36
	v_lshlrev_b64 v[32:33], 1, v[32:33]
	v_lshl_add_u64 v[34:35], s[46:47], 0, v[32:33]
	v_lshl_add_u64 v[122:123], s[48:49], 0, v[32:33]
	v_add3_u32 v32, 0, v37, v38
	ds_read_b128 v[56:59], v32
	ds_read_b128 v[60:63], v32 offset:16
	v_and_b32_e32 v32, 64, v164
	v_add_u32_e32 v32, 64, v32
	v_xor_b32_e32 v33, 1, v164
	v_cmp_lt_i32_e32 vcc, v33, v32
	v_readlane_b32 s64, v254, 46
	v_lshlrev_b32_e32 v48, 6, v36
	v_cndmask_b32_e32 v33, v164, v33, vcc
	v_lshlrev_b32_e32 v77, 2, v33
	v_xor_b32_e32 v33, 2, v164
	v_cmp_lt_i32_e32 vcc, v33, v32
	v_readlane_b32 s68, v254, 50
	v_readlane_b32 s69, v254, 51
	v_cndmask_b32_e32 v33, v164, v33, vcc
	v_lshlrev_b32_e32 v75, 2, v33
	v_xor_b32_e32 v33, 4, v164
	v_cmp_lt_i32_e32 vcc, v33, v32
	s_waitcnt lgkmcnt(0)
	v_lshlrev_b32_e32 v132, 16, v62
	v_and_b32_e32 v133, 0xffff0000, v62
	v_cndmask_b32_e32 v32, v164, v33, vcc
	v_lshlrev_b32_e32 v73, 2, v32
	global_load_dwordx4 v[52:55], v[34:35], off
	s_nop 0
	global_load_dwordx4 v[32:35], v[34:35], off offset:16
	s_nop 0
	global_load_dwordx4 v[36:39], v48, s[68:69] offset:48
	global_load_dwordx4 v[40:43], v48, s[68:69] offset:32
	global_load_dwordx4 v[44:47], v48, s[68:69] offset:16
	s_nop 0
	global_load_dwordx4 v[48:51], v48, s[68:69]
	v_lshlrev_b32_e32 v130, 16, v63
	v_and_b32_e32 v131, 0xffff0000, v63
	v_pk_mul_f32 v[62:63], v[132:133], v[132:133]
	v_pk_mul_f32 v[134:135], v[130:131], v[130:131]
	v_readlane_b32 s65, v254, 47
	v_readlane_b32 s66, v254, 48
	v_readlane_b32 s67, v254, 49
	v_readlane_b32 s70, v254, 52
	v_readlane_b32 s71, v254, 53
	v_readlane_b32 s72, v254, 54
	v_readlane_b32 s73, v254, 55
	v_readlane_b32 s74, v254, 56
	v_readlane_b32 s75, v254, 57
	v_readlane_b32 s76, v254, 58
	v_readlane_b32 s77, v254, 59
	v_readlane_b32 s78, v254, 60
	v_readlane_b32 s79, v254, 61
	s_waitcnt vmcnt(5)
	v_lshlrev_b32_e32 v150, 16, v55
	s_waitcnt vmcnt(4)
	v_lshlrev_b32_e32 v136, 16, v34
	v_and_b32_e32 v137, 0xffff0000, v34
	v_mul_f32_e32 v34, 0xbfb8aa3b, v136
	v_exp_f32_e32 v138, v34
	v_mul_f32_e32 v34, 0xbfb8aa3b, v137
	v_exp_f32_e32 v139, v34
	v_lshlrev_b32_e32 v142, 16, v33
	v_and_b32_e32 v143, 0xffff0000, v33
	v_mul_f32_e32 v33, 0xbfb8aa3b, v142
	v_pk_add_f32 v[138:139], v[138:139], 1.0 op_sel_hi:[1,0]
	v_exp_f32_e32 v144, v33
	v_mul_f32_e32 v33, 0xbfb8aa3b, v143
	v_exp_f32_e32 v145, v33
	v_lshlrev_b32_e32 v146, 16, v32
	v_rcp_f32_e32 v139, v139
	s_nop 0
	v_pk_add_f32 v[144:145], v[144:145], 1.0 op_sel_hi:[1,0]
	v_and_b32_e32 v147, 0xffff0000, v32
	v_rcp_f32_e32 v138, v138
	s_nop 0
	v_pk_mul_f32 v[136:137], v[138:139], v[136:137]
	v_lshlrev_b32_e32 v138, 16, v61
	v_and_b32_e32 v139, 0xffff0000, v61
	v_rcp_f32_e32 v145, v145
	s_nop 0
	v_mul_f32_e32 v32, 0xbfb8aa3b, v146
	v_exp_f32_e32 v32, v32
	v_and_b32_e32 v151, 0xffff0000, v55
	v_rcp_f32_e32 v144, v144
	s_nop 0
	v_mul_f32_e32 v33, 0xbfb8aa3b, v147
	v_exp_f32_e32 v33, v33
	v_lshlrev_b32_e32 v154, 16, v54
	v_and_b32_e32 v155, 0xffff0000, v54
	v_lshlrev_b32_e32 v158, 16, v53
	v_pk_add_f32 v[32:33], v[32:33], 1.0 op_sel_hi:[1,0]
	v_and_b32_e32 v159, 0xffff0000, v53
	v_lshlrev_b32_e32 v168, 16, v52
	v_and_b32_e32 v169, 0xffff0000, v52
	v_pk_mul_f32 v[142:143], v[144:145], v[142:143]
	v_rcp_f32_e32 v33, v33
	s_nop 0
	v_lshlrev_b32_e32 v144, 16, v60
	v_and_b32_e32 v145, 0xffff0000, v60
	v_pk_mul_f32 v[60:61], v[144:145], v[144:145]
	v_rcp_f32_e32 v32, v32
	s_nop 0
	v_mul_f32_e32 v34, 0xbfb8aa3b, v150
	v_exp_f32_e32 v152, v34
	v_mul_f32_e32 v34, 0xbfb8aa3b, v151
	v_exp_f32_e32 v153, v34
	v_pk_mul_f32 v[32:33], v[32:33], v[146:147]
	v_lshlrev_b32_e32 v146, 16, v59
	v_and_b32_e32 v147, 0xffff0000, v59
	v_pk_add_f32 v[152:153], v[152:153], 1.0 op_sel_hi:[1,0]
	v_pk_mul_f32 v[148:149], v[146:147], v[146:147]
	v_pk_mul_f32 v[140:141], v[138:139], v[138:139]
	v_rcp_f32_e32 v153, v153
	s_nop 0
	s_nop 0
	v_rcp_f32_e32 v152, v152
	s_nop 0
	v_mul_f32_e32 v34, 0xbfb8aa3b, v154
	v_exp_f32_e32 v54, v34
	v_mul_f32_e32 v34, 0xbfb8aa3b, v155
	v_exp_f32_e32 v55, v34
	v_pk_mul_f32 v[150:151], v[152:153], v[150:151]
	v_lshlrev_b32_e32 v152, 16, v58
	v_and_b32_e32 v153, 0xffff0000, v58
	v_pk_add_f32 v[54:55], v[54:55], 1.0 op_sel_hi:[1,0]
	v_pk_mul_f32 v[58:59], v[152:153], v[152:153]
	s_nop 0
	v_rcp_f32_e32 v55, v55
	s_nop 0
	s_nop 0
	v_rcp_f32_e32 v54, v54
	s_nop 0
	v_mul_f32_e32 v34, 0xbfb8aa3b, v158
	v_exp_f32_e32 v166, v34
	v_mul_f32_e32 v34, 0xbfb8aa3b, v159
	v_exp_f32_e32 v167, v34
	v_pk_mul_f32 v[54:55], v[54:55], v[154:155]
	v_lshlrev_b32_e32 v154, 16, v57
	v_and_b32_e32 v155, 0xffff0000, v57
	v_pk_add_f32 v[166:167], v[166:167], 1.0 op_sel_hi:[1,0]
	v_pk_mul_f32 v[156:157], v[154:155], v[154:155]
	s_nop 0
	v_rcp_f32_e32 v167, v167
	s_nop 0
	s_nop 0
	v_rcp_f32_e32 v166, v166
	s_nop 0
	v_mul_f32_e32 v34, 0xbfb8aa3b, v168
	v_exp_f32_e32 v52, v34
	v_mul_f32_e32 v34, 0xbfb8aa3b, v169
	v_exp_f32_e32 v53, v34
	v_pk_mul_f32 v[158:159], v[166:167], v[158:159]
	v_lshlrev_b32_e32 v166, 16, v56
	v_and_b32_e32 v167, 0xffff0000, v56
	v_pk_add_f32 v[52:53], v[52:53], 1.0 op_sel_hi:[1,0]
	v_pk_mul_f32 v[56:57], v[166:167], v[166:167]
	s_nop 0
	v_rcp_f32_e32 v53, v53
	s_nop 0
	s_nop 0
	v_rcp_f32_e32 v52, v52
	s_nop 0
	v_add_f32_e32 v34, v56, v57
	v_add_f32_e32 v34, v156, v34
	v_add_f32_e32 v34, v157, v34
	v_add_f32_e32 v34, v58, v34
	v_add_f32_e32 v34, v59, v34
	v_add_f32_e32 v34, v148, v34
	v_add_f32_e32 v34, v149, v34
	v_add_f32_e32 v34, v60, v34
	v_add_f32_e32 v34, v61, v34
	v_add_f32_e32 v34, v140, v34
	v_add_f32_e32 v34, v141, v34
	v_add_f32_e32 v34, v62, v34
	v_add_f32_e32 v34, v63, v34
	v_add_f32_e32 v34, v134, v34
	v_add_f32_e32 v34, v135, v34
	ds_bpermute_b32 v56, v77, v34
	v_pk_mul_f32 v[52:53], v[52:53], v[168:169]
	s_waitcnt lgkmcnt(0)
	v_add_f32_e32 v34, v34, v56
	ds_bpermute_b32 v56, v75, v34
	s_waitcnt lgkmcnt(0)
	v_add_f32_e32 v34, v34, v56
	ds_bpermute_b32 v56, v73, v34
	s_waitcnt lgkmcnt(0)
	v_add_f32_e32 v34, v34, v56
	v_fmamk_f32 v34, v34, 0x3c000000, v162
	v_cmp_gt_f32_e32 vcc, s6, v34
	v_mul_f32_e32 v56, 0x4b800000, v34
	s_nop 0
	v_cndmask_b32_e32 v34, v34, v56, vcc
	v_rsq_f32_e32 v34, v34
	s_nop 0
	v_mul_f32_e32 v56, 0x45800000, v34
	v_cndmask_b32_e32 v56, v34, v56, vcc
	v_pk_mul_f32 v[58:59], v[56:57], v[166:167] op_sel_hi:[0,1]
	s_waitcnt vmcnt(0)
	v_pk_mul_f32 v[48:49], v[48:49], v[58:59]
	s_nop 0
	v_pk_mul_f32 v[48:49], v[52:53], v[48:49]
	v_pk_mul_f32 v[52:53], v[56:57], v[154:155] op_sel_hi:[0,1]
	v_pk_mul_f32 v[50:51], v[50:51], v[52:53]
	v_cvt_pk_bf16_f32 v48, v48, v49
	v_pk_mul_f32 v[50:51], v[158:159], v[50:51]
	s_nop 0
	v_cvt_pk_bf16_f32 v49, v50, v51
	v_pk_mul_f32 v[50:51], v[56:57], v[152:153] op_sel_hi:[0,1]
	v_pk_mul_f32 v[44:45], v[44:45], v[50:51]
	s_nop 0
	v_pk_mul_f32 v[44:45], v[54:55], v[44:45]
	s_nop 0
	v_cvt_pk_bf16_f32 v50, v44, v45
	v_pk_mul_f32 v[44:45], v[56:57], v[146:147] op_sel_hi:[0,1]
	v_pk_mul_f32 v[44:45], v[46:47], v[44:45]
	s_nop 0
	v_pk_mul_f32 v[44:45], v[150:151], v[44:45]
	s_nop 0
	v_cvt_pk_bf16_f32 v51, v44, v45
	v_pk_mul_f32 v[44:45], v[56:57], v[144:145] op_sel_hi:[0,1]
	v_pk_mul_f32 v[40:41], v[40:41], v[44:45]
	s_nop 0
	v_pk_mul_f32 v[32:33], v[32:33], v[40:41]
	v_pk_mul_f32 v[40:41], v[56:57], v[138:139] op_sel_hi:[0,1]
	v_pk_mul_f32 v[40:41], v[42:43], v[40:41]
	v_cvt_pk_bf16_f32 v32, v32, v33
	v_pk_mul_f32 v[40:41], v[142:143], v[40:41]
	v_pk_mul_f32 v[42:43], v[56:57], v[130:131] op_sel_hi:[0,1]
	v_cvt_pk_bf16_f32 v33, v40, v41
	v_pk_mul_f32 v[40:41], v[56:57], v[132:133] op_sel_hi:[0,1]
	v_pk_mul_f32 v[36:37], v[36:37], v[40:41]
	v_pk_mul_f32 v[38:39], v[38:39], v[42:43]
	v_pk_mul_f32 v[36:37], v[136:137], v[36:37]
	s_nop 0
	v_cvt_pk_bf16_f32 v34, v36, v37
	v_lshlrev_b32_e32 v36, 16, v35
	v_and_b32_e32 v37, 0xffff0000, v35
	v_mul_f32_e32 v35, 0xbfb8aa3b, v36
	v_exp_f32_e32 v40, v35
	v_mul_f32_e32 v35, 0xbfb8aa3b, v37
	v_exp_f32_e32 v41, v35
	s_nop 0
	v_pk_add_f32 v[40:41], v[40:41], 1.0 op_sel_hi:[1,0]
	s_nop 0
	s_nop 0
	v_rcp_f32_e32 v41, v41
	s_nop 0
	s_nop 0
	v_rcp_f32_e32 v40, v40
	s_nop 0
	v_pk_mul_f32 v[36:37], v[40:41], v[36:37]
	s_nop 0
	v_pk_mul_f32 v[36:37], v[36:37], v[38:39]
	s_nop 0
	v_cvt_pk_bf16_f32 v35, v36, v37
	global_store_dwordx4 v[122:123], v[48:51], off
	global_store_dwordx4 v[122:123], v[32:35], off offset:16

.LBB0_1098:
	s_lshl_b32 s10, s0, 4
	s_add_i32 s10, s1, s10
	s_ashr_i32 s11, s10, 31
	s_mul_i32 s29, s10, 0x12000
	s_mul_hi_i32 s26, s10, 0x12000
	s_add_u32 s30, s19, s29
	s_addc_u32 s31, s42, s26
	s_lshl_b64 s[10:11], s[10:11], 2
	s_add_u32 s10, s43, s10
	s_addc_u32 s11, s4, s11
	global_load_dword v56, v125, s[10:11] sc1
	v_add_u32_e32 v40, 0x2000, v113
	v_add_u32_e32 v41, 0x8000, v113
	v_add_u32_e32 v38, 0xa000, v113
	v_add_u32_e32 v39, 0xc000, v113
	v_add_u32_e32 v34, 0xe000, v113
	v_add_u32_e32 v35, 0x10000, v113
	global_load_dwordx4 v[166:169], v113, s[30:31]
	global_load_dwordx4 v[170:173], v40, s[30:31]
	global_load_dwordx4 v[174:177], v41, s[30:31]
	global_load_dwordx4 v[178:181], v38, s[30:31]
	global_load_dwordx4 v[182:185], v39, s[30:31]
	global_load_dwordx4 v[186:189], v34, s[30:31]
	global_load_dwordx4 v[190:193], v35, s[30:31]
	v_lshl_add_u64 v[226:227], s[30:31], 0, v[72:73]
	v_lshl_add_u64 v[226:227], v[226:227], 0, v[68:69]
	s_mov_b64 s[10:11], 0x4000
	v_lshl_add_u64 v[226:227], v[226:227], 0, s[10:11]
	global_load_dwordx2 v[214:215], v[226:227], off
	global_load_dwordx2 v[216:217], v[226:227], off offset:32
	global_load_dwordx2 v[218:219], v[226:227], off offset:64
	global_load_dwordx2 v[220:221], v[226:227], off offset:96
	v_ashrrev_i32_e32 v32, 4, v67
	v_mul_u32_u24_e32 v32, 0x110, v32
	v_and_b32_e32 v33, 15, v67
	v_lshl_add_u32 v32, v33, 4, v32
	v_ashrrev_i32_e32 v33, 3, v67
	v_lshl_add_u32 v33, v33, 4, v113
	s_waitcnt lgkmcnt(0)
	s_barrier
	s_waitcnt vmcnt(10)
	ds_write_b128 v32, v[166:169] offset:0
	s_waitcnt vmcnt(9)
	ds_write_b128 v32, v[170:173] offset:8704
	s_waitcnt vmcnt(8)
	ds_write_b128 v32, v[174:177] offset:17408
	s_waitcnt vmcnt(7)
	ds_write_b128 v32, v[178:181] offset:26112
	s_waitcnt vmcnt(6)
	ds_write_b128 v33, v[182:185] offset:34816
	s_waitcnt vmcnt(5)
	ds_write_b128 v33, v[186:189] offset:44032
	s_waitcnt vmcnt(4)
	ds_write_b128 v33, v[190:193] offset:53248
	v_add_u32_e32 v57, v110, v68
	v_add_u32_e32 v36, v66, v109
	s_waitcnt lgkmcnt(0)
	s_barrier
	ds_read_b128 v[52:55], v36 offset:62464
	ds_read_b128 v[48:51], v36 offset:62528
	ds_read_b128 v[44:47], v36 offset:62592
	ds_read_b128 v[40:43], v36 offset:62656
	ds_read_b128 v[138:141], v114 offset:0
	ds_read_b128 v[142:145], v114 offset:64
	ds_read_b128 v[146:149], v114 offset:128
	ds_read_b128 v[150:153], v114 offset:192
	ds_read_b128 v[194:197], v114 offset:4352
	ds_read_b128 v[198:201], v114 offset:4416
	ds_read_b128 v[202:205], v114 offset:4480
	ds_read_b128 v[206:209], v114 offset:4544
	s_waitcnt lgkmcnt(7)
	v_mfma_f32_16x16x32_bf16 v[154:157], v[138:141], v[52:55], 0
	s_waitcnt lgkmcnt(6)
	v_mfma_f32_16x16x32_bf16 v[154:157], v[142:145], v[48:51], v[154:157]
	s_waitcnt lgkmcnt(5)
	v_mfma_f32_16x16x32_bf16 v[154:157], v[146:149], v[44:47], v[154:157]
	s_waitcnt lgkmcnt(4)
	v_mfma_f32_16x16x32_bf16 v[154:157], v[150:153], v[40:43], v[154:157]
	ds_read_b128 v[138:141], v114 offset:8704
	ds_read_b128 v[142:145], v114 offset:8768
	ds_read_b128 v[146:149], v114 offset:8832
	ds_read_b128 v[150:153], v114 offset:8896
	s_waitcnt lgkmcnt(7)
	v_mfma_f32_16x16x32_bf16 v[210:213], v[194:197], v[52:55], 0
	s_waitcnt lgkmcnt(6)
	v_mfma_f32_16x16x32_bf16 v[210:213], v[198:201], v[48:51], v[210:213]
	s_waitcnt lgkmcnt(5)
	v_mfma_f32_16x16x32_bf16 v[210:213], v[202:205], v[44:47], v[210:213]
	s_waitcnt lgkmcnt(4)
	v_mfma_f32_16x16x32_bf16 v[210:213], v[206:209], v[40:43], v[210:213]
	s_waitcnt vmcnt(3)
	v_lshlrev_b32_e32 v222, 16, v214
	v_and_b32_e32 v223, 0xffff0000, v214
	v_lshlrev_b32_e32 v224, 16, v215
	v_and_b32_e32 v225, 0xffff0000, v215
	v_pk_add_f32 v[154:155], v[222:223], v[154:155] neg_lo:[0,1] neg_hi:[0,1]
	v_pk_add_f32 v[156:157], v[224:225], v[156:157] neg_lo:[0,1] neg_hi:[0,1]
	v_cvt_pk_bf16_f32 v154, v154, v155
	v_cvt_pk_bf16_f32 v155, v156, v157
	ds_write_b64 v57, v[154:155]
	ds_read_b128 v[194:197], v114 offset:13056
	ds_read_b128 v[198:201], v114 offset:13120
	ds_read_b128 v[202:205], v114 offset:13184
	ds_read_b128 v[206:209], v114 offset:13248
	s_waitcnt lgkmcnt(8)
	v_mfma_f32_16x16x32_bf16 v[154:157], v[138:141], v[52:55], 0
	s_waitcnt lgkmcnt(7)
	v_mfma_f32_16x16x32_bf16 v[154:157], v[142:145], v[48:51], v[154:157]
	s_waitcnt lgkmcnt(6)
	v_mfma_f32_16x16x32_bf16 v[154:157], v[146:149], v[44:47], v[154:157]
	s_waitcnt lgkmcnt(5)
	v_mfma_f32_16x16x32_bf16 v[154:157], v[150:153], v[40:43], v[154:157]
	s_waitcnt vmcnt(2)
	v_lshlrev_b32_e32 v222, 16, v216
	v_and_b32_e32 v223, 0xffff0000, v216
	v_lshlrev_b32_e32 v224, 16, v217
	v_and_b32_e32 v225, 0xffff0000, v217
	v_pk_add_f32 v[210:211], v[222:223], v[210:211] neg_lo:[0,1] neg_hi:[0,1]
	v_pk_add_f32 v[212:213], v[224:225], v[212:213] neg_lo:[0,1] neg_hi:[0,1]
	v_cvt_pk_bf16_f32 v210, v210, v211
	v_cvt_pk_bf16_f32 v211, v212, v213
	ds_write_b64 v57, v[210:211] offset:32
	s_waitcnt lgkmcnt(4)
	v_mfma_f32_16x16x32_bf16 v[210:213], v[194:197], v[52:55], 0
	s_waitcnt lgkmcnt(3)
	v_mfma_f32_16x16x32_bf16 v[210:213], v[198:201], v[48:51], v[210:213]
	s_waitcnt lgkmcnt(2)
	v_mfma_f32_16x16x32_bf16 v[210:213], v[202:205], v[44:47], v[210:213]
	s_waitcnt lgkmcnt(1)
	v_mfma_f32_16x16x32_bf16 v[210:213], v[206:209], v[40:43], v[210:213]
	s_waitcnt vmcnt(1)
	v_lshlrev_b32_e32 v222, 16, v218
	v_and_b32_e32 v223, 0xffff0000, v218
	v_lshlrev_b32_e32 v224, 16, v219
	v_and_b32_e32 v225, 0xffff0000, v219
	v_pk_add_f32 v[154:155], v[222:223], v[154:155] neg_lo:[0,1] neg_hi:[0,1]
	v_pk_add_f32 v[156:157], v[224:225], v[156:157] neg_lo:[0,1] neg_hi:[0,1]
	v_cvt_pk_bf16_f32 v154, v154, v155
	v_cvt_pk_bf16_f32 v155, v156, v157
	ds_write_b64 v57, v[154:155] offset:64
	s_nop 1
	s_waitcnt vmcnt(0)
	v_lshlrev_b32_e32 v222, 16, v220
	v_and_b32_e32 v223, 0xffff0000, v220
	v_lshlrev_b32_e32 v224, 16, v221
	v_and_b32_e32 v225, 0xffff0000, v221
	v_pk_add_f32 v[210:211], v[222:223], v[210:211] neg_lo:[0,1] neg_hi:[0,1]
	v_pk_add_f32 v[212:213], v[224:225], v[212:213] neg_lo:[0,1] neg_hi:[0,1]
	v_cvt_pk_bf16_f32 v210, v210, v211
	v_cvt_pk_bf16_f32 v211, v212, v213
	ds_write_b64 v57, v[210:211] offset:96
	v_add_u32_e32 v226, v110, v109
	s_waitcnt lgkmcnt(0)
	s_barrier
	ds_read_b128 v[36:39], v226
	ds_read_b128 v[32:35], v226 offset:64
	ds_read_b128 v[138:141], v114 offset:17408
	ds_read_b128 v[142:145], v114 offset:17472
	ds_read_b128 v[146:149], v114 offset:17536
	ds_read_b128 v[150:153], v114 offset:17600
	ds_read_b128 v[154:157], v115 offset:34816
	ds_read_b128 v[194:197], v115 offset:34880
	ds_read_b128 v[198:201], v114 offset:21760
	ds_read_b128 v[202:205], v114 offset:21824
	ds_read_b128 v[206:209], v114 offset:21888
	ds_read_b128 v[210:213], v114 offset:21952
	ds_read_b128 v[214:217], v115 offset:37120
	ds_read_b128 v[218:221], v115 offset:37184
	s_waitcnt lgkmcnt(11)
	v_mfma_f32_16x16x32_bf16 v[222:225], v[138:141], v[52:55], 0
	s_waitcnt lgkmcnt(10)
	v_mfma_f32_16x16x32_bf16 v[222:225], v[142:145], v[48:51], v[222:225]
	s_waitcnt lgkmcnt(9)
	v_mfma_f32_16x16x32_bf16 v[222:225], v[146:149], v[44:47], v[222:225]
	s_waitcnt lgkmcnt(8)
	v_mfma_f32_16x16x32_bf16 v[222:225], v[150:153], v[40:43], v[222:225]
	s_waitcnt lgkmcnt(7)
	v_mfma_f32_16x16x32_bf16 v[222:225], v[154:157], v[36:39], v[222:225]
	s_waitcnt lgkmcnt(6)
	v_mfma_f32_16x16x32_bf16 v[222:225], v[194:197], v[32:35], v[222:225]
	ds_read_b128 v[138:141], v114 offset:26112
	ds_read_b128 v[142:145], v114 offset:26176
	ds_read_b128 v[146:149], v114 offset:26240
	ds_read_b128 v[150:153], v114 offset:26304
	ds_read_b128 v[154:157], v115 offset:39424
	ds_read_b128 v[194:197], v115 offset:39488
	s_waitcnt lgkmcnt(11)
	v_mfma_f32_16x16x32_bf16 v[244:247], v[198:201], v[52:55], 0
	s_waitcnt lgkmcnt(10)
	v_mfma_f32_16x16x32_bf16 v[244:247], v[202:205], v[48:51], v[244:247]
	s_waitcnt lgkmcnt(9)
	v_mfma_f32_16x16x32_bf16 v[244:247], v[206:209], v[44:47], v[244:247]
	s_waitcnt lgkmcnt(8)
	v_mfma_f32_16x16x32_bf16 v[244:247], v[210:213], v[40:43], v[244:247]
	s_waitcnt lgkmcnt(7)
	v_mfma_f32_16x16x32_bf16 v[244:247], v[214:217], v[36:39], v[244:247]
	s_waitcnt lgkmcnt(6)
	v_mfma_f32_16x16x32_bf16 v[244:247], v[218:221], v[32:35], v[244:247]
	ds_read_b128 v[198:201], v114 offset:30464
	ds_read_b128 v[202:205], v114 offset:30528
	ds_read_b128 v[206:209], v114 offset:30592
	ds_read_b128 v[210:213], v114 offset:30656
	ds_read_b128 v[214:217], v115 offset:41728
	ds_read_b128 v[218:221], v115 offset:41792
	s_waitcnt lgkmcnt(11)
	v_mfma_f32_16x16x32_bf16 v[248:251], v[138:141], v[52:55], 0
	s_waitcnt lgkmcnt(10)
	v_mfma_f32_16x16x32_bf16 v[248:251], v[142:145], v[48:51], v[248:251]
	s_waitcnt lgkmcnt(9)
	v_mfma_f32_16x16x32_bf16 v[248:251], v[146:149], v[44:47], v[248:251]
	s_waitcnt lgkmcnt(8)
	v_mfma_f32_16x16x32_bf16 v[248:251], v[150:153], v[40:43], v[248:251]
	s_waitcnt lgkmcnt(7)
	v_mfma_f32_16x16x32_bf16 v[248:251], v[154:157], v[36:39], v[248:251]
	s_waitcnt lgkmcnt(6)
	v_mfma_f32_16x16x32_bf16 v[248:251], v[194:197], v[32:35], v[248:251]
	v_cvt_pk_bf16_f32 v57, v222, s0
	ds_write_b16 v116, v57
	v_cvt_pk_bf16_f32 v57, v223, s0
	ds_write_b16 v117, v57
	v_cvt_pk_bf16_f32 v57, v224, s0
	ds_write_b16 v117, v57 offset:272
	v_cvt_pk_bf16_f32 v57, v225, s0
	ds_write_b16 v117, v57 offset:544
	v_cvt_pk_bf16_f32 v57, v244, s0
	ds_write_b16 v117, v57 offset:4080
	v_cvt_pk_bf16_f32 v57, v245, s0
	ds_write_b16 v117, v57 offset:4352
	v_cvt_pk_bf16_f32 v57, v246, s0
	ds_write_b16 v117, v57 offset:4624
	v_cvt_pk_bf16_f32 v57, v247, s0
	ds_write_b16 v117, v57 offset:4896
	v_pk_mul_f32 v[30:31], v[30:31], v[56:57] op_sel_hi:[1,0]
	v_pk_mul_f32 v[28:29], v[28:29], v[56:57] op_sel_hi:[1,0]
	v_pk_mul_f32 v[22:23], v[22:23], v[56:57] op_sel_hi:[1,0]
	v_pk_mul_f32 v[20:21], v[20:21], v[56:57] op_sel_hi:[1,0]
	v_pk_mul_f32 v[2:3], v[2:3], v[56:57] op_sel_hi:[1,0]
	v_pk_mul_f32 v[0:1], v[0:1], v[56:57] op_sel_hi:[1,0]
	v_pk_mul_f32 v[18:19], v[18:19], v[56:57] op_sel_hi:[1,0]
	v_pk_mul_f32 v[16:17], v[16:17], v[56:57] op_sel_hi:[1,0]
	v_pk_mul_f32 v[6:7], v[6:7], v[56:57] op_sel_hi:[1,0]
	v_pk_mul_f32 v[4:5], v[4:5], v[56:57] op_sel_hi:[1,0]
	v_mul_f32_e64 v14, v14, v56
	v_mul_f32_e64 v15, v15, v56
	v_pk_mul_f32 v[12:13], v[12:13], v[56:57] op_sel_hi:[1,0]
	v_pk_mul_f32 v[10:11], v[10:11], v[56:57] op_sel_hi:[1,0]
	v_pk_mul_f32 v[8:9], v[8:9], v[56:57] op_sel_hi:[1,0]
	v_pk_mul_f32 v[26:27], v[26:27], v[56:57] op_sel_hi:[1,0]
	v_pk_mul_f32 v[24:25], v[24:25], v[56:57] op_sel_hi:[1,0]
	s_waitcnt lgkmcnt(13)
	v_mfma_f32_16x16x32_bf16 v[222:225], v[198:201], v[52:55], 0
	s_waitcnt lgkmcnt(12)
	v_mfma_f32_16x16x32_bf16 v[222:225], v[202:205], v[48:51], v[222:225]
	s_waitcnt lgkmcnt(11)
	v_mfma_f32_16x16x32_bf16 v[222:225], v[206:209], v[44:47], v[222:225]
	s_waitcnt lgkmcnt(10)
	v_mfma_f32_16x16x32_bf16 v[222:225], v[210:213], v[40:43], v[222:225]
	s_waitcnt lgkmcnt(9)
	v_mfma_f32_16x16x32_bf16 v[222:225], v[214:217], v[36:39], v[222:225]
	s_waitcnt lgkmcnt(8)
	v_mfma_f32_16x16x32_bf16 v[222:225], v[218:221], v[32:35], v[222:225]
	v_cvt_pk_bf16_f32 v57, v248, s0
	ds_write_b16 v117, v57 offset:8432
	v_cvt_pk_bf16_f32 v57, v249, s0
	ds_write_b16 v117, v57 offset:8704
	v_cvt_pk_bf16_f32 v57, v250, s0
	ds_write_b16 v117, v57 offset:8976
	v_cvt_pk_bf16_f32 v57, v251, s0
	ds_write_b16 v117, v57 offset:9248
	ds_read_b128 v[138:141], v115 offset:44032
	ds_read_b128 v[142:145], v115 offset:44096
	ds_read_b128 v[146:149], v115 offset:46336
	ds_read_b128 v[150:153], v115 offset:46400
	ds_read_b128 v[154:157], v115 offset:48640
	ds_read_b128 v[194:197], v115 offset:48704
	ds_read_b128 v[198:201], v115 offset:50944
	ds_read_b128 v[202:205], v115 offset:51008
	v_cvt_pk_bf16_f32 v57, v222, s0
	ds_write_b16 v117, v57 offset:12784
	v_cvt_pk_bf16_f32 v57, v223, s0
	ds_write_b16 v117, v57 offset:13056
	v_cvt_pk_bf16_f32 v57, v224, s0
	ds_write_b16 v117, v57 offset:13328
	v_cvt_pk_bf16_f32 v57, v225, s0
	ds_write_b16 v117, v57 offset:13600
	s_waitcnt lgkmcnt(11)
	v_mfma_f32_16x16x32_bf16 v[28:31], v[138:141], v[36:39], v[28:31]
	s_waitcnt lgkmcnt(10)
	v_mfma_f32_16x16x32_bf16 v[28:31], v[142:145], v[32:35], v[28:31]
	ds_read_b128 v[138:141], v115 offset:53248
	ds_read_b128 v[142:145], v115 offset:53312
	s_waitcnt lgkmcnt(11)
	v_mfma_f32_16x16x32_bf16 v[20:23], v[146:149], v[36:39], v[20:23]
	s_waitcnt lgkmcnt(10)
	v_mfma_f32_16x16x32_bf16 v[20:23], v[150:153], v[32:35], v[20:23]
	ds_read_b128 v[146:149], v115 offset:55552
	ds_read_b128 v[150:153], v115 offset:55616
	s_waitcnt lgkmcnt(11)
	v_mfma_f32_16x16x32_bf16 v[0:3], v[154:157], v[36:39], v[0:3]
	s_waitcnt lgkmcnt(10)
	v_mfma_f32_16x16x32_bf16 v[0:3], v[194:197], v[32:35], v[0:3]
	ds_read_b128 v[154:157], v115 offset:57856
	ds_read_b128 v[194:197], v115 offset:57920
	s_waitcnt lgkmcnt(11)
	v_mfma_f32_16x16x32_bf16 v[16:19], v[198:201], v[36:39], v[16:19]
	s_waitcnt lgkmcnt(10)
	v_mfma_f32_16x16x32_bf16 v[16:19], v[202:205], v[32:35], v[16:19]
	ds_read_b128 v[198:201], v115 offset:60160
	ds_read_b128 v[202:205], v115 offset:60224
	s_waitcnt lgkmcnt(7)
	v_mfma_f32_16x16x32_bf16 v[4:7], v[138:141], v[36:39], v[4:7]
	s_waitcnt lgkmcnt(6)
	v_mfma_f32_16x16x32_bf16 v[4:7], v[142:145], v[32:35], v[4:7]
	s_waitcnt lgkmcnt(5)
	v_mfma_f32_16x16x32_bf16 v[12:15], v[146:149], v[36:39], v[12:15]
	s_waitcnt lgkmcnt(4)
	v_mfma_f32_16x16x32_bf16 v[12:15], v[150:153], v[32:35], v[12:15]
	s_waitcnt lgkmcnt(3)
	v_mfma_f32_16x16x32_bf16 v[8:11], v[154:157], v[36:39], v[8:11]
	s_waitcnt lgkmcnt(2)
	v_mfma_f32_16x16x32_bf16 v[8:11], v[194:197], v[32:35], v[8:11]
	s_waitcnt lgkmcnt(1)
	v_mfma_f32_16x16x32_bf16 v[24:27], v[198:201], v[36:39], v[24:27]
	s_waitcnt lgkmcnt(0)
	s_waitcnt lgkmcnt(0)
	s_barrier
	v_mfma_f32_16x16x32_bf16 v[24:27], v[202:205], v[32:35], v[24:27]
	v_add_u32_e32 v36, v66, v68
	v_cvt_pk_bf16_f32 v32, v28, v29
	v_cvt_pk_bf16_f32 v33, v30, v31
	v_cvt_pk_bf16_f32 v34, v20, v21
	v_cvt_pk_bf16_f32 v35, v22, v23
	v_add_u32_e32 v36, 0xf000, v36
	ds_write2_b64 v36, v[32:33], v[34:35] offset0:128 offset1:132
	v_cvt_pk_bf16_f32 v32, v0, v1
	v_cvt_pk_bf16_f32 v33, v2, v3
	v_cvt_pk_bf16_f32 v34, v16, v17
	v_cvt_pk_bf16_f32 v35, v18, v19
	ds_write2_b64 v36, v[32:33], v[34:35] offset0:136 offset1:140
	v_cvt_pk_bf16_f32 v32, v4, v5
	v_cvt_pk_bf16_f32 v33, v6, v7
	v_cvt_pk_bf16_f32 v34, v12, v13
	v_cvt_pk_bf16_f32 v35, v14, v15
	ds_write2_b64 v36, v[32:33], v[34:35] offset0:144 offset1:148
	v_cvt_pk_bf16_f32 v32, v8, v9
	v_cvt_pk_bf16_f32 v33, v10, v11
	v_cvt_pk_bf16_f32 v34, v24, v25
	v_cvt_pk_bf16_f32 v35, v26, v27
	ds_write2_b64 v36, v[32:33], v[34:35] offset0:152 offset1:156
	s_and_saveexec_b64 s[30:31], s[40:41]
	s_cbranch_execz .LBB0_1097
	v_and_b32_e32 v32, 64, v164
	v_add_u32_e32 v32, 64, v32
	v_xor_b32_e32 v33, 1, v164
	v_cmp_lt_i32_e32 vcc, v33, v32
	ds_read_b128 v[52:55], v118
	ds_read_b128 v[60:63], v118 offset:16
	v_cndmask_b32_e32 v33, v164, v33, vcc
	v_lshlrev_b32_e32 v121, 2, v33
	v_xor_b32_e32 v33, 2, v164
	v_cmp_lt_i32_e32 vcc, v33, v32
	s_waitcnt lgkmcnt(0)
	v_lshlrev_b32_e32 v80, 16, v62
	v_and_b32_e32 v81, 0xffff0000, v62
	v_cndmask_b32_e32 v33, v164, v33, vcc
	v_lshlrev_b32_e32 v120, 2, v33
	v_xor_b32_e32 v33, 4, v164
	v_cmp_lt_i32_e32 vcc, v33, v32
	v_lshlrev_b32_e32 v78, 16, v63
	v_and_b32_e32 v79, 0xffff0000, v63
	v_cndmask_b32_e32 v32, v164, v33, vcc
	v_lshlrev_b32_e32 v119, 2, v32
	v_lshl_add_u32 v32, s0, 6, v112
	v_ashrrev_i32_e32 v33, 31, v32
	v_lshlrev_b64 v[76:77], 12, v[32:33]
	v_lshl_or_b32 v76, v70, 1, v76
	v_lshl_add_u64 v[32:33], s[46:47], 0, v[76:77]
	global_load_dwordx4 v[56:59], v[32:33], off
	s_nop 0
	global_load_dwordx4 v[32:35], v[32:33], off offset:16
	s_nop 0
	global_load_dwordx4 v[36:39], v[74:75], off offset:48
	global_load_dwordx4 v[40:43], v[74:75], off offset:32
	global_load_dwordx4 v[44:47], v[74:75], off offset:16
	global_load_dwordx4 v[48:51], v[74:75], off
	v_pk_mul_f32 v[62:63], v[80:81], v[80:81]
	v_pk_mul_f32 v[82:83], v[78:79], v[78:79]
	s_waitcnt vmcnt(5)
	v_lshlrev_b32_e32 v130, 16, v56
	s_waitcnt vmcnt(4)
	v_lshlrev_b32_e32 v84, 16, v34
	v_and_b32_e32 v85, 0xffff0000, v34
	v_mul_f32_e32 v34, 0xbfb8aa3b, v84
	v_exp_f32_e32 v86, v34
	v_mul_f32_e32 v34, 0xbfb8aa3b, v85
	v_exp_f32_e32 v87, v34
	v_and_b32_e32 v131, 0xffff0000, v56
	v_pk_add_f32 v[86:87], v[86:87], 1.0 op_sel_hi:[1,0]
	s_nop 0
	s_nop 0
	v_rcp_f32_e32 v87, v87
	s_nop 0
	s_nop 0
	v_lshlrev_b32_e32 v88, 16, v33
	v_and_b32_e32 v89, 0xffff0000, v33
	v_mul_f32_e32 v33, 0xbfb8aa3b, v88
	v_exp_f32_e32 v90, v33
	v_mul_f32_e32 v33, 0xbfb8aa3b, v89
	v_exp_f32_e32 v91, v33
	v_rcp_f32_e32 v86, v86
	s_nop 0
	v_pk_mul_f32 v[84:85], v[86:87], v[84:85]
	v_lshlrev_b32_e32 v86, 16, v61
	v_pk_add_f32 v[90:91], v[90:91], 1.0 op_sel_hi:[1,0]
	v_and_b32_e32 v87, 0xffff0000, v61
	v_pk_mul_f32 v[92:93], v[86:87], v[86:87]
	v_rcp_f32_e32 v91, v91
	s_nop 0
	s_nop 0
	v_lshlrev_b32_e32 v94, 16, v32
	v_and_b32_e32 v95, 0xffff0000, v32
	v_rcp_f32_e32 v90, v90
	s_nop 0
	v_mul_f32_e32 v32, 0xbfb8aa3b, v94
	v_mul_f32_e32 v33, 0xbfb8aa3b, v95
	v_exp_f32_e32 v32, v32
	v_exp_f32_e32 v33, v33
	v_pk_mul_f32 v[88:89], v[90:91], v[88:89]
	v_lshlrev_b32_e32 v90, 16, v60
	v_and_b32_e32 v91, 0xffff0000, v60
	v_pk_add_f32 v[32:33], v[32:33], 1.0 op_sel_hi:[1,0]
	v_pk_mul_f32 v[60:61], v[90:91], v[90:91]
	s_nop 0
	v_rcp_f32_e32 v33, v33
	s_nop 0
	s_nop 0
	v_lshlrev_b32_e32 v98, 16, v59
	v_rcp_f32_e32 v32, v32
	s_nop 0
	v_and_b32_e32 v99, 0xffff0000, v59
	v_mul_f32_e32 v34, 0xbfb8aa3b, v98
	v_exp_f32_e32 v100, v34
	v_mul_f32_e32 v34, 0xbfb8aa3b, v99
	v_exp_f32_e32 v101, v34
	v_pk_mul_f32 v[32:33], v[32:33], v[94:95]
	v_lshlrev_b32_e32 v94, 16, v55
	v_and_b32_e32 v95, 0xffff0000, v55
	v_pk_add_f32 v[100:101], v[100:101], 1.0 op_sel_hi:[1,0]
	v_pk_mul_f32 v[96:97], v[94:95], v[94:95]
	s_nop 0
	v_rcp_f32_e32 v101, v101
	s_nop 0
	s_nop 0
	v_lshlrev_b32_e32 v102, 16, v58
	v_rcp_f32_e32 v100, v100
	s_nop 0
	v_and_b32_e32 v103, 0xffff0000, v58
	v_mul_f32_e32 v34, 0xbfb8aa3b, v102
	v_exp_f32_e32 v58, v34
	v_mul_f32_e32 v34, 0xbfb8aa3b, v103
	v_exp_f32_e32 v59, v34
	v_pk_mul_f32 v[98:99], v[100:101], v[98:99]
	v_lshlrev_b32_e32 v100, 16, v54
	v_and_b32_e32 v101, 0xffff0000, v54
	v_pk_add_f32 v[58:59], v[58:59], 1.0 op_sel_hi:[1,0]
	v_pk_mul_f32 v[54:55], v[100:101], v[100:101]
	s_nop 0
	v_rcp_f32_e32 v59, v59
	s_nop 0
	s_nop 0
	v_lshlrev_b32_e32 v106, 16, v57
	v_rcp_f32_e32 v58, v58
	s_nop 0
	v_and_b32_e32 v107, 0xffff0000, v57
	v_mul_f32_e32 v34, 0xbfb8aa3b, v106
	v_exp_f32_e32 v122, v34
	v_mul_f32_e32 v34, 0xbfb8aa3b, v107
	v_exp_f32_e32 v123, v34
	v_pk_mul_f32 v[58:59], v[58:59], v[102:103]
	v_lshlrev_b32_e32 v102, 16, v53
	v_and_b32_e32 v103, 0xffff0000, v53
	v_pk_add_f32 v[122:123], v[122:123], 1.0 op_sel_hi:[1,0]
	v_pk_mul_f32 v[104:105], v[102:103], v[102:103]
	s_nop 0
	v_rcp_f32_e32 v123, v123
	s_nop 0
	s_nop 0
	v_rcp_f32_e32 v122, v122
	s_nop 0
	v_mul_f32_e32 v34, 0xbfb8aa3b, v130
	v_exp_f32_e32 v56, v34
	v_mul_f32_e32 v34, 0xbfb8aa3b, v131
	v_exp_f32_e32 v57, v34
	v_pk_mul_f32 v[106:107], v[122:123], v[106:107]
	v_lshlrev_b32_e32 v122, 16, v52
	v_and_b32_e32 v123, 0xffff0000, v52
	v_pk_add_f32 v[56:57], v[56:57], 1.0 op_sel_hi:[1,0]
	v_pk_mul_f32 v[52:53], v[122:123], v[122:123]
	s_nop 0
	v_rcp_f32_e32 v57, v57
	s_nop 0
	s_nop 0
	v_rcp_f32_e32 v56, v56
	s_nop 0
	v_add_f32_e32 v34, v52, v53
	v_add_f32_e32 v34, v104, v34
	v_add_f32_e32 v34, v105, v34
	v_add_f32_e32 v34, v54, v34
	v_add_f32_e32 v34, v55, v34
	v_add_f32_e32 v34, v96, v34
	v_add_f32_e32 v34, v97, v34
	v_add_f32_e32 v34, v60, v34
	v_add_f32_e32 v34, v61, v34
	v_add_f32_e32 v34, v92, v34
	v_add_f32_e32 v34, v93, v34
	v_add_f32_e32 v34, v62, v34
	v_add_f32_e32 v34, v63, v34
	v_add_f32_e32 v34, v82, v34
	v_add_f32_e32 v34, v83, v34
	ds_bpermute_b32 v52, v121, v34
	v_pk_mul_f32 v[56:57], v[56:57], v[130:131]
	s_waitcnt lgkmcnt(0)
	v_add_f32_e32 v34, v34, v52
	ds_bpermute_b32 v52, v120, v34
	s_waitcnt lgkmcnt(0)
	v_add_f32_e32 v34, v34, v52
	ds_bpermute_b32 v52, v119, v34
	s_waitcnt lgkmcnt(0)
	v_add_f32_e32 v34, v34, v52
	v_fmamk_f32 v34, v34, 0x3c000000, v162
	v_cmp_gt_f32_e32 vcc, s6, v34
	v_mul_f32_e32 v52, 0x4b800000, v34
	s_nop 0
	v_cndmask_b32_e32 v34, v34, v52, vcc
	v_rsq_f32_e32 v34, v34
	s_nop 0
	v_mul_f32_e32 v52, 0x45800000, v34
	v_cndmask_b32_e32 v52, v34, v52, vcc
	v_pk_mul_f32 v[54:55], v[52:53], v[122:123] op_sel_hi:[0,1]
	s_waitcnt vmcnt(0)
	v_pk_mul_f32 v[48:49], v[48:49], v[54:55]
	v_pk_mul_f32 v[54:55], v[52:53], v[102:103] op_sel_hi:[0,1]
	v_pk_mul_f32 v[50:51], v[50:51], v[54:55]
	v_pk_mul_f32 v[48:49], v[56:57], v[48:49]
	v_pk_mul_f32 v[50:51], v[106:107], v[50:51]
	v_cvt_pk_bf16_f32 v48, v48, v49
	v_cvt_pk_bf16_f32 v49, v50, v51
	v_pk_mul_f32 v[50:51], v[52:53], v[100:101] op_sel_hi:[0,1]
	v_pk_mul_f32 v[44:45], v[44:45], v[50:51]
	s_nop 0
	v_pk_mul_f32 v[44:45], v[58:59], v[44:45]
	s_nop 0
	v_cvt_pk_bf16_f32 v50, v44, v45
	v_pk_mul_f32 v[44:45], v[52:53], v[94:95] op_sel_hi:[0,1]
	v_pk_mul_f32 v[44:45], v[46:47], v[44:45]
	s_nop 0
	v_pk_mul_f32 v[44:45], v[98:99], v[44:45]
	s_nop 0
	v_cvt_pk_bf16_f32 v51, v44, v45
	v_pk_mul_f32 v[44:45], v[52:53], v[90:91] op_sel_hi:[0,1]
	v_pk_mul_f32 v[40:41], v[40:41], v[44:45]
	s_nop 0
	v_pk_mul_f32 v[32:33], v[32:33], v[40:41]
	v_pk_mul_f32 v[40:41], v[52:53], v[86:87] op_sel_hi:[0,1]
	v_pk_mul_f32 v[40:41], v[42:43], v[40:41]
	v_cvt_pk_bf16_f32 v32, v32, v33
	v_pk_mul_f32 v[40:41], v[88:89], v[40:41]
	v_pk_mul_f32 v[42:43], v[52:53], v[78:79] op_sel_hi:[0,1]
	v_cvt_pk_bf16_f32 v33, v40, v41
	v_pk_mul_f32 v[40:41], v[52:53], v[80:81] op_sel_hi:[0,1]
	v_pk_mul_f32 v[36:37], v[36:37], v[40:41]
	v_pk_mul_f32 v[38:39], v[38:39], v[42:43]
	v_pk_mul_f32 v[36:37], v[84:85], v[36:37]
	s_nop 0
	v_cvt_pk_bf16_f32 v34, v36, v37
	v_lshlrev_b32_e32 v36, 16, v35
	v_and_b32_e32 v37, 0xffff0000, v35
	v_mul_f32_e32 v35, 0xbfb8aa3b, v36
	v_exp_f32_e32 v40, v35
	v_mul_f32_e32 v35, 0xbfb8aa3b, v37
	v_exp_f32_e32 v41, v35
	s_nop 0
	v_pk_add_f32 v[40:41], v[40:41], 1.0 op_sel_hi:[1,0]
	s_nop 0
	s_nop 0
	v_rcp_f32_e32 v41, v41
	s_nop 0
	s_nop 0
	v_rcp_f32_e32 v40, v40
	s_nop 0
	v_pk_mul_f32 v[36:37], v[40:41], v[36:37]
	s_nop 0
	v_pk_mul_f32 v[36:37], v[36:37], v[38:39]
	s_nop 0
	v_cvt_pk_bf16_f32 v35, v36, v37
	v_lshl_add_u64 v[36:37], s[48:49], 0, v[76:77]
	global_store_dwordx4 v[36:37], v[48:51], off
	global_store_dwordx4 v[36:37], v[32:35], off offset:16
	s_branch .LBB0_1097
